# FFN1 gate/up SwiGLU epilogue: separate copy for rs==1 (rows already normalised) without the 64 packed multiplies by 1.0 (bit-identical results)
# speedup vs baseline: 1.0050x; 1.0050x over previous
.LBB0_262:
	s_and_b64 vcc, exec, s[0:1]
	s_cbranch_vccnz .Lswiglu_nors
	s_lshl_b32 s19, s44, 2
	v_and_b32_e32 v146, 15, v145
	s_add_i32 s11, s11, s19
	v_lshl_add_u32 v144, v146, 2, s11
	v_mov_b32_e32 v140, 1.0
	s_and_b64 vcc, exec, s[0:1]
	v_mov_b32_e32 v142, 1.0
	s_cbranch_vccnz .LBB0_264
	ds_read_b32 v142, v144

.Lswiglu_join:
	s_cbranch_vccnz .LBB0_249
	s_andn2_b64 vcc, exec, s[2:3]
	s_cbranch_vccnz .LBB0_248
	s_barrier
	s_branch .LBB0_248

.Lswn_264:
	s_lshl_b32 s11, s49, 7
	v_lshrrev_b32_e32 v138, 1, v145
	v_and_or_b32 v138, v138, 24, s11
	s_lshl_b32 s11, s24, 8
	s_add_i32 s11, s11, s44
	s_waitcnt lgkmcnt(0)
	v_or_b32_e32 v145, s11, v146
	v_mul_f32_e32 v146, 0xbfb8aa3b, v124
	v_mul_f32_e32 v147, 0xbfb8aa3b, v125
	v_exp_f32_e32 v146, v146
	v_exp_f32_e32 v147, v147
	v_add_f32_e32 v146, 1.0, v146
	v_add_f32_e32 v147, 1.0, v147
	v_rcp_f32_e32 v146, v146
	v_rcp_f32_e32 v147, v147
	s_nop 0
	v_pk_mul_f32 v[124:125], v[124:125], v[146:147]
	v_or_b32_e32 v138, s45, v138
	v_pk_mul_f32 v[120:121], v[120:121], v[124:125]
	v_mov_b64_e32 v[124:125], v[126:127]
	v_ashrrev_i32_e32 v139, 31, v138
	v_mul_f32_e32 v126, 0xbfb8aa3b, v124
	v_mul_f32_e32 v127, 0xbfb8aa3b, v125
	v_exp_f32_e32 v126, v126
	v_exp_f32_e32 v127, v127
	s_and_b64 vcc, exec, s[0:1]
	v_add_f32_e32 v126, 1.0, v126
	v_add_f32_e32 v127, 1.0, v127
	v_rcp_f32_e32 v126, v126
	v_rcp_f32_e32 v127, v127
	s_nop 0
	v_pk_mul_f32 v[124:125], v[124:125], v[126:127]
	s_nop 0
	v_pk_mul_f32 v[122:123], v[122:123], v[124:125]
	v_mul_f32_e32 v124, 0xbfb8aa3b, v116
	v_mul_f32_e32 v125, 0xbfb8aa3b, v117
	v_exp_f32_e32 v124, v124
	v_exp_f32_e32 v125, v125
	v_add_f32_e32 v124, 1.0, v124
	v_add_f32_e32 v125, 1.0, v125
	v_rcp_f32_e32 v124, v124
	v_rcp_f32_e32 v125, v125
	s_nop 0
	v_pk_mul_f32 v[116:117], v[116:117], v[124:125]
	s_nop 0
	v_pk_mul_f32 v[116:117], v[112:113], v[116:117]
	v_mov_b64_e32 v[112:113], v[118:119]
	s_nop 0
	v_mul_f32_e32 v118, 0xbfb8aa3b, v112
	v_mul_f32_e32 v119, 0xbfb8aa3b, v113
	v_exp_f32_e32 v118, v118
	v_exp_f32_e32 v119, v119
	v_add_f32_e32 v118, 1.0, v118
	v_add_f32_e32 v119, 1.0, v119
	v_rcp_f32_e32 v118, v118
	v_rcp_f32_e32 v119, v119
	s_nop 0
	v_pk_mul_f32 v[112:113], v[112:113], v[118:119]
	s_nop 0
	v_pk_mul_f32 v[118:119], v[114:115], v[112:113]
	v_mov_b64_e32 v[112:113], s[6:7]
	v_mad_i64_i32 v[112:113], s[26:27], v145, s30, v[112:113]
	v_lshl_add_u64 v[124:125], v[138:139], 1, v[112:113]
	v_cvt_pk_bf16_f32 v112, v120, v121
	v_cvt_pk_bf16_f32 v113, v122, v123
	v_cvt_pk_bf16_f32 v114, v116, v117
	v_cvt_pk_bf16_f32 v115, v118, v119
	global_store_dwordx4 v[124:125], v[112:115], off
	s_cbranch_vccnz .Lswn_266
	ds_read_b32 v140, v144 offset:64
.Lswn_266:
	s_waitcnt lgkmcnt(0)
	v_mov_b64_e32 v[112:113], v[108:109]
	v_mul_f32_e32 v108, 0xbfb8aa3b, v112
	v_exp_f32_e32 v109, v108
	s_nop 0
	v_add_f32_e32 v109, 1.0, v109
	v_rcp_f32_e32 v114, v109
	v_mul_f32_e32 v109, 0xbfb8aa3b, v113
	v_exp_f32_e32 v109, v109
	v_or_b32_e32 v116, 16, v145
	v_add_f32_e32 v109, 1.0, v109
	v_rcp_f32_e32 v115, v109
	v_mul_f32_e32 v109, 0xbfb8aa3b, v110
	v_exp_f32_e32 v109, v109
	v_mov_b32_e32 v108, 1.0
	v_pk_mul_f32 v[112:113], v[112:113], v[114:115]
	s_and_b64 vcc, exec, s[0:1]
	v_add_f32_e32 v109, 1.0, v109
	v_pk_mul_f32 v[104:105], v[104:105], v[112:113]
	v_rcp_f32_e32 v112, v109
	v_mul_f32_e32 v109, 0xbfb8aa3b, v111
	v_exp_f32_e32 v109, v109
	s_nop 0
	v_add_f32_e32 v109, 1.0, v109
	v_rcp_f32_e32 v113, v109
	v_mul_f32_e32 v109, 0xbfb8aa3b, v100
	v_exp_f32_e32 v109, v109
	v_pk_mul_f32 v[110:111], v[110:111], v[112:113]
	s_nop 0
	v_pk_mul_f32 v[106:107], v[106:107], v[110:111]
	v_add_f32_e32 v109, 1.0, v109
	v_rcp_f32_e32 v110, v109
	v_mul_f32_e32 v109, 0xbfb8aa3b, v101
	v_exp_f32_e32 v109, v109
	s_nop 0
	v_add_f32_e32 v109, 1.0, v109
	v_rcp_f32_e32 v111, v109
	s_nop 0
	v_pk_mul_f32 v[100:101], v[100:101], v[110:111]
	s_nop 0
	v_pk_mul_f32 v[100:101], v[96:97], v[100:101]
	v_mov_b64_e32 v[96:97], v[102:103]
	s_nop 0
	v_mul_f32_e32 v102, 0xbfb8aa3b, v96
	v_mul_f32_e32 v103, 0xbfb8aa3b, v97
	v_exp_f32_e32 v102, v102
	v_exp_f32_e32 v103, v103
	v_add_f32_e32 v102, 1.0, v102
	v_add_f32_e32 v103, 1.0, v103
	v_rcp_f32_e32 v102, v102
	v_rcp_f32_e32 v103, v103
	s_nop 0
	v_pk_mul_f32 v[96:97], v[96:97], v[102:103]
	s_nop 0
	v_pk_mul_f32 v[102:103], v[98:99], v[96:97]
	v_mov_b64_e32 v[96:97], s[6:7]
	v_mad_i64_i32 v[96:97], s[26:27], v116, s30, v[96:97]
	v_lshl_add_u64 v[110:111], v[138:139], 1, v[96:97]
	v_cvt_pk_bf16_f32 v96, v104, v105
	v_cvt_pk_bf16_f32 v97, v106, v107
	v_cvt_pk_bf16_f32 v98, v100, v101
	v_cvt_pk_bf16_f32 v99, v102, v103
	global_store_dwordx4 v[110:111], v[96:99], off
	s_nop 1
	v_mov_b32_e32 v96, 1.0
	s_cbranch_vccnz .Lswn_268
	ds_read_b32 v96, v144 offset:128
.Lswn_268:
	v_or_b32_e32 v97, 32, v145
	s_waitcnt lgkmcnt(0)
	v_mul_f32_e32 v98, 0xbfb8aa3b, v92
	v_mul_f32_e32 v99, 0xbfb8aa3b, v93
	v_exp_f32_e32 v98, v98
	v_exp_f32_e32 v99, v99
	v_add_f32_e32 v98, 1.0, v98
	v_add_f32_e32 v99, 1.0, v99
	v_rcp_f32_e32 v98, v98
	v_rcp_f32_e32 v99, v99
	s_and_b64 vcc, exec, s[0:1]
	v_pk_mul_f32 v[92:93], v[92:93], v[98:99]
	s_nop 0
	v_pk_mul_f32 v[88:89], v[88:89], v[92:93]
	v_mov_b64_e32 v[92:93], v[94:95]
	s_nop 0
	v_mul_f32_e32 v94, 0xbfb8aa3b, v92
	v_mul_f32_e32 v95, 0xbfb8aa3b, v93
	v_exp_f32_e32 v94, v94
	v_exp_f32_e32 v95, v95
	v_add_f32_e32 v94, 1.0, v94
	v_add_f32_e32 v95, 1.0, v95
	v_rcp_f32_e32 v94, v94
	v_rcp_f32_e32 v95, v95
	s_nop 0
	v_pk_mul_f32 v[92:93], v[92:93], v[94:95]
	s_nop 0
	v_pk_mul_f32 v[90:91], v[90:91], v[92:93]
	v_mul_f32_e32 v92, 0xbfb8aa3b, v84
	v_mul_f32_e32 v93, 0xbfb8aa3b, v85
	v_exp_f32_e32 v92, v92
	v_exp_f32_e32 v93, v93
	v_add_f32_e32 v92, 1.0, v92
	v_add_f32_e32 v93, 1.0, v93
	v_rcp_f32_e32 v92, v92
	v_rcp_f32_e32 v93, v93
	s_nop 0
	v_pk_mul_f32 v[84:85], v[84:85], v[92:93]
	s_nop 0
	v_pk_mul_f32 v[84:85], v[80:81], v[84:85]
	v_mov_b64_e32 v[80:81], v[86:87]
	s_nop 0
	v_mul_f32_e32 v86, 0xbfb8aa3b, v80
	v_mul_f32_e32 v87, 0xbfb8aa3b, v81
	v_exp_f32_e32 v86, v86
	v_exp_f32_e32 v87, v87
	v_add_f32_e32 v86, 1.0, v86
	v_add_f32_e32 v87, 1.0, v87
	v_rcp_f32_e32 v86, v86
	v_rcp_f32_e32 v87, v87
	s_nop 0
	v_pk_mul_f32 v[80:81], v[80:81], v[86:87]
	s_nop 0
	v_pk_mul_f32 v[86:87], v[82:83], v[80:81]
	v_mov_b64_e32 v[80:81], s[6:7]
	v_mad_i64_i32 v[80:81], s[26:27], v97, s30, v[80:81]
	v_lshl_add_u64 v[92:93], v[138:139], 1, v[80:81]
	v_cvt_pk_bf16_f32 v80, v88, v89
	v_cvt_pk_bf16_f32 v81, v90, v91
	v_cvt_pk_bf16_f32 v82, v84, v85
	v_cvt_pk_bf16_f32 v83, v86, v87
	global_store_dwordx4 v[92:93], v[80:83], off
	s_cbranch_vccnz .Lswn_270
	ds_read_b32 v108, v144 offset:192
.Lswn_270:
	s_waitcnt lgkmcnt(0)
	v_mov_b64_e32 v[80:81], v[76:77]
	v_mul_f32_e32 v76, 0xbfb8aa3b, v80
	v_exp_f32_e32 v77, v76
	s_nop 0
	v_add_f32_e32 v77, 1.0, v77
	v_rcp_f32_e32 v82, v77
	v_mul_f32_e32 v77, 0xbfb8aa3b, v81
	v_exp_f32_e32 v77, v77
	v_or_b32_e32 v84, 48, v145
	v_add_f32_e32 v77, 1.0, v77
	v_rcp_f32_e32 v83, v77
	v_mul_f32_e32 v77, 0xbfb8aa3b, v78
	v_exp_f32_e32 v77, v77
	v_mov_b32_e32 v76, 1.0
	v_pk_mul_f32 v[80:81], v[80:81], v[82:83]
	s_and_b64 vcc, exec, s[0:1]
	v_add_f32_e32 v77, 1.0, v77
	v_pk_mul_f32 v[72:73], v[72:73], v[80:81]
	v_rcp_f32_e32 v80, v77
	v_mul_f32_e32 v77, 0xbfb8aa3b, v79
	v_exp_f32_e32 v77, v77
	s_nop 0
	v_add_f32_e32 v77, 1.0, v77
	v_rcp_f32_e32 v81, v77
	v_mul_f32_e32 v77, 0xbfb8aa3b, v68
	v_exp_f32_e32 v77, v77
	v_pk_mul_f32 v[78:79], v[78:79], v[80:81]
	s_nop 0
	v_pk_mul_f32 v[74:75], v[74:75], v[78:79]
	v_add_f32_e32 v77, 1.0, v77
	v_rcp_f32_e32 v78, v77
	v_mul_f32_e32 v77, 0xbfb8aa3b, v69
	v_exp_f32_e32 v77, v77
	s_nop 0
	v_add_f32_e32 v77, 1.0, v77
	v_rcp_f32_e32 v79, v77
	s_nop 0
	v_pk_mul_f32 v[68:69], v[68:69], v[78:79]
	s_nop 0
	v_pk_mul_f32 v[68:69], v[64:65], v[68:69]
	v_mov_b64_e32 v[64:65], v[70:71]
	s_nop 0
	v_mul_f32_e32 v70, 0xbfb8aa3b, v64
	v_mul_f32_e32 v71, 0xbfb8aa3b, v65
	v_exp_f32_e32 v70, v70
	v_exp_f32_e32 v71, v71
	v_add_f32_e32 v70, 1.0, v70
	v_add_f32_e32 v71, 1.0, v71
	v_rcp_f32_e32 v70, v70
	v_rcp_f32_e32 v71, v71
	s_nop 0
	v_pk_mul_f32 v[64:65], v[64:65], v[70:71]
	s_nop 0
	v_pk_mul_f32 v[70:71], v[66:67], v[64:65]
	v_mov_b64_e32 v[64:65], s[6:7]
	v_mad_i64_i32 v[64:65], s[26:27], v84, s30, v[64:65]
	v_lshl_add_u64 v[78:79], v[138:139], 1, v[64:65]
	v_cvt_pk_bf16_f32 v64, v72, v73
	v_cvt_pk_bf16_f32 v65, v74, v75
	v_cvt_pk_bf16_f32 v66, v68, v69
	v_cvt_pk_bf16_f32 v67, v70, v71
	global_store_dwordx4 v[78:79], v[64:67], off
	s_nop 1
	v_mov_b32_e32 v64, 1.0
	s_cbranch_vccnz .Lswn_272
	ds_read_b32 v64, v144 offset:512
.Lswn_272:
	v_add_u32_e32 v65, 0x80, v145
	s_waitcnt lgkmcnt(0)
	v_mul_f32_e32 v66, 0xbfb8aa3b, v60
	v_mul_f32_e32 v67, 0xbfb8aa3b, v61
	v_exp_f32_e32 v66, v66
	v_exp_f32_e32 v67, v67
	v_add_f32_e32 v66, 1.0, v66
	v_add_f32_e32 v67, 1.0, v67
	v_rcp_f32_e32 v66, v66
	v_rcp_f32_e32 v67, v67
	s_and_b64 vcc, exec, s[0:1]
	v_pk_mul_f32 v[60:61], v[60:61], v[66:67]
	s_nop 0
	v_pk_mul_f32 v[56:57], v[56:57], v[60:61]
	v_mov_b64_e32 v[60:61], v[62:63]
	s_nop 0
	v_mul_f32_e32 v62, 0xbfb8aa3b, v60
	v_mul_f32_e32 v63, 0xbfb8aa3b, v61
	v_exp_f32_e32 v62, v62
	v_exp_f32_e32 v63, v63
	v_add_f32_e32 v62, 1.0, v62
	v_add_f32_e32 v63, 1.0, v63
	v_rcp_f32_e32 v62, v62
	v_rcp_f32_e32 v63, v63
	s_nop 0
	v_pk_mul_f32 v[60:61], v[60:61], v[62:63]
	s_nop 0
	v_pk_mul_f32 v[58:59], v[58:59], v[60:61]
	v_mul_f32_e32 v60, 0xbfb8aa3b, v52
	v_mul_f32_e32 v61, 0xbfb8aa3b, v53
	v_exp_f32_e32 v60, v60
	v_exp_f32_e32 v61, v61
	v_add_f32_e32 v60, 1.0, v60
	v_add_f32_e32 v61, 1.0, v61
	v_rcp_f32_e32 v60, v60
	v_rcp_f32_e32 v61, v61
	s_nop 0
	v_pk_mul_f32 v[52:53], v[52:53], v[60:61]
	s_nop 0
	v_pk_mul_f32 v[52:53], v[48:49], v[52:53]
	v_mov_b64_e32 v[48:49], v[54:55]
	s_nop 0
	v_mul_f32_e32 v54, 0xbfb8aa3b, v48
	v_mul_f32_e32 v55, 0xbfb8aa3b, v49
	v_exp_f32_e32 v54, v54
	v_exp_f32_e32 v55, v55
	v_add_f32_e32 v54, 1.0, v54
	v_add_f32_e32 v55, 1.0, v55
	v_rcp_f32_e32 v54, v54
	v_rcp_f32_e32 v55, v55
	s_nop 0
	v_pk_mul_f32 v[48:49], v[48:49], v[54:55]
	s_nop 0
	v_pk_mul_f32 v[54:55], v[50:51], v[48:49]
	v_mov_b64_e32 v[48:49], s[6:7]
	v_mad_i64_i32 v[48:49], s[26:27], v65, s30, v[48:49]
	v_lshl_add_u64 v[60:61], v[138:139], 1, v[48:49]
	v_cvt_pk_bf16_f32 v48, v56, v57
	v_cvt_pk_bf16_f32 v49, v58, v59
	v_cvt_pk_bf16_f32 v50, v52, v53
	v_cvt_pk_bf16_f32 v51, v54, v55
	global_store_dwordx4 v[60:61], v[48:51], off
	s_cbranch_vccnz .Lswn_274
	ds_read_b32 v76, v144 offset:576
.Lswn_274:
	s_waitcnt lgkmcnt(0)
	v_mov_b64_e32 v[48:49], v[44:45]
	v_mul_f32_e32 v44, 0xbfb8aa3b, v48
	v_exp_f32_e32 v45, v44
	s_nop 0
	v_add_f32_e32 v45, 1.0, v45
	v_rcp_f32_e32 v50, v45
	v_mul_f32_e32 v45, 0xbfb8aa3b, v49
	v_exp_f32_e32 v45, v45
	v_add_u32_e32 v52, 0x90, v145
	v_add_f32_e32 v45, 1.0, v45
	v_rcp_f32_e32 v51, v45
	v_mul_f32_e32 v45, 0xbfb8aa3b, v46
	v_exp_f32_e32 v45, v45
	v_mov_b32_e32 v44, 1.0
	v_pk_mul_f32 v[48:49], v[48:49], v[50:51]
	s_and_b64 vcc, exec, s[0:1]
	v_add_f32_e32 v45, 1.0, v45
	v_pk_mul_f32 v[40:41], v[40:41], v[48:49]
	v_rcp_f32_e32 v48, v45
	v_mul_f32_e32 v45, 0xbfb8aa3b, v47
	v_exp_f32_e32 v45, v45
	s_nop 0
	v_add_f32_e32 v45, 1.0, v45
	v_rcp_f32_e32 v49, v45
	v_mul_f32_e32 v45, 0xbfb8aa3b, v36
	v_exp_f32_e32 v45, v45
	v_pk_mul_f32 v[46:47], v[46:47], v[48:49]
	s_nop 0
	v_pk_mul_f32 v[42:43], v[42:43], v[46:47]
	v_add_f32_e32 v45, 1.0, v45
	v_rcp_f32_e32 v46, v45
	v_mul_f32_e32 v45, 0xbfb8aa3b, v37
	v_exp_f32_e32 v45, v45
	s_nop 0
	v_add_f32_e32 v45, 1.0, v45
	v_rcp_f32_e32 v47, v45
	s_nop 0
	v_pk_mul_f32 v[36:37], v[36:37], v[46:47]
	s_nop 0
	v_pk_mul_f32 v[36:37], v[32:33], v[36:37]
	v_mov_b64_e32 v[32:33], v[38:39]
	s_nop 0
	v_mul_f32_e32 v38, 0xbfb8aa3b, v32
	v_mul_f32_e32 v39, 0xbfb8aa3b, v33
	v_exp_f32_e32 v38, v38
	v_exp_f32_e32 v39, v39
	v_add_f32_e32 v38, 1.0, v38
	v_add_f32_e32 v39, 1.0, v39
	v_rcp_f32_e32 v38, v38
	v_rcp_f32_e32 v39, v39
	s_nop 0
	v_pk_mul_f32 v[32:33], v[32:33], v[38:39]
	s_nop 0
	v_pk_mul_f32 v[38:39], v[34:35], v[32:33]
	v_mov_b64_e32 v[32:33], s[6:7]
	v_mad_i64_i32 v[32:33], s[26:27], v52, s30, v[32:33]
	v_lshl_add_u64 v[46:47], v[138:139], 1, v[32:33]
	v_cvt_pk_bf16_f32 v32, v40, v41
	v_cvt_pk_bf16_f32 v33, v42, v43
	v_cvt_pk_bf16_f32 v34, v36, v37
	v_cvt_pk_bf16_f32 v35, v38, v39
	global_store_dwordx4 v[46:47], v[32:35], off
	s_nop 1
	v_mov_b32_e32 v32, 1.0
	s_cbranch_vccnz .Lswn_276
	ds_read_b32 v32, v144 offset:640
.Lswn_276:
	v_add_u32_e32 v33, 0xa0, v145
	s_waitcnt lgkmcnt(0)
	v_mul_f32_e32 v34, 0xbfb8aa3b, v28
	v_mul_f32_e32 v35, 0xbfb8aa3b, v29
	v_exp_f32_e32 v34, v34
	v_exp_f32_e32 v35, v35
	v_add_f32_e32 v34, 1.0, v34
	v_add_f32_e32 v35, 1.0, v35
	v_rcp_f32_e32 v34, v34
	v_rcp_f32_e32 v35, v35
	s_and_b64 vcc, exec, s[0:1]
	v_pk_mul_f32 v[28:29], v[28:29], v[34:35]
	s_nop 0
	v_pk_mul_f32 v[24:25], v[24:25], v[28:29]
	v_mov_b64_e32 v[28:29], v[30:31]
	s_nop 0
	v_mul_f32_e32 v30, 0xbfb8aa3b, v28
	v_mul_f32_e32 v31, 0xbfb8aa3b, v29
	v_exp_f32_e32 v30, v30
	v_exp_f32_e32 v31, v31
	v_add_f32_e32 v30, 1.0, v30
	v_add_f32_e32 v31, 1.0, v31
	v_rcp_f32_e32 v30, v30
	v_rcp_f32_e32 v31, v31
	s_nop 0
	v_pk_mul_f32 v[28:29], v[28:29], v[30:31]
	s_nop 0
	v_pk_mul_f32 v[26:27], v[26:27], v[28:29]
	v_mul_f32_e32 v28, 0xbfb8aa3b, v20
	v_mul_f32_e32 v29, 0xbfb8aa3b, v21
	v_exp_f32_e32 v28, v28
	v_exp_f32_e32 v29, v29
	v_add_f32_e32 v28, 1.0, v28
	v_add_f32_e32 v29, 1.0, v29
	v_rcp_f32_e32 v28, v28
	v_rcp_f32_e32 v29, v29
	s_nop 0
	v_pk_mul_f32 v[20:21], v[20:21], v[28:29]
	s_nop 0
	v_pk_mul_f32 v[20:21], v[16:17], v[20:21]
	v_mov_b64_e32 v[16:17], v[22:23]
	s_nop 0
	v_mul_f32_e32 v22, 0xbfb8aa3b, v16
	v_mul_f32_e32 v23, 0xbfb8aa3b, v17
	v_exp_f32_e32 v22, v22
	v_exp_f32_e32 v23, v23
	v_add_f32_e32 v22, 1.0, v22
	v_add_f32_e32 v23, 1.0, v23
	v_rcp_f32_e32 v22, v22
	v_rcp_f32_e32 v23, v23
	s_nop 0
	v_pk_mul_f32 v[16:17], v[16:17], v[22:23]
	s_nop 0
	v_pk_mul_f32 v[22:23], v[18:19], v[16:17]
	v_mov_b64_e32 v[16:17], s[6:7]
	v_mad_i64_i32 v[16:17], s[26:27], v33, s30, v[16:17]
	v_lshl_add_u64 v[28:29], v[138:139], 1, v[16:17]
	v_cvt_pk_bf16_f32 v16, v24, v25
	v_cvt_pk_bf16_f32 v17, v26, v27
	v_cvt_pk_bf16_f32 v18, v20, v21
	v_cvt_pk_bf16_f32 v19, v22, v23
	global_store_dwordx4 v[28:29], v[16:19], off
	s_cbranch_vccnz .Lswn_278
	ds_read_b32 v44, v144 offset:704
.Lswn_278:
	s_waitcnt lgkmcnt(0)
	v_mul_f32_e32 v16, 0xbfb8aa3b, v12
	v_mul_f32_e32 v17, 0xbfb8aa3b, v13
	v_exp_f32_e32 v16, v16
	v_exp_f32_e32 v17, v17
	v_add_f32_e32 v16, 1.0, v16
	v_add_f32_e32 v17, 1.0, v17
	v_rcp_f32_e32 v16, v16
	v_rcp_f32_e32 v17, v17
	v_add_u32_e32 v18, 0xb0, v145
	v_pk_mul_f32 v[12:13], v[12:13], v[16:17]
	s_andn2_b64 vcc, exec, s[4:5]
	v_pk_mul_f32 v[8:9], v[8:9], v[12:13]
	v_mov_b64_e32 v[12:13], v[14:15]
	s_nop 0
	v_mul_f32_e32 v14, 0xbfb8aa3b, v12
	v_mul_f32_e32 v15, 0xbfb8aa3b, v13
	v_exp_f32_e32 v14, v14
	v_exp_f32_e32 v15, v15
	v_add_f32_e32 v14, 1.0, v14
	v_add_f32_e32 v15, 1.0, v15
	v_rcp_f32_e32 v14, v14
	v_rcp_f32_e32 v15, v15
	s_nop 0
	v_pk_mul_f32 v[12:13], v[12:13], v[14:15]
	s_nop 0
	v_pk_mul_f32 v[10:11], v[10:11], v[12:13]
	v_mul_f32_e32 v12, 0xbfb8aa3b, v4
	v_mul_f32_e32 v13, 0xbfb8aa3b, v5
	v_exp_f32_e32 v12, v12
	v_exp_f32_e32 v13, v13
	v_add_f32_e32 v12, 1.0, v12
	v_add_f32_e32 v13, 1.0, v13
	v_rcp_f32_e32 v12, v12
	v_rcp_f32_e32 v13, v13
	s_nop 0
	v_pk_mul_f32 v[4:5], v[4:5], v[12:13]
	s_nop 0
	v_pk_mul_f32 v[4:5], v[0:1], v[4:5]
	v_mov_b64_e32 v[0:1], v[6:7]
	s_nop 0
	v_mul_f32_e32 v6, 0xbfb8aa3b, v0
	v_mul_f32_e32 v7, 0xbfb8aa3b, v1
	v_exp_f32_e32 v6, v6
	v_exp_f32_e32 v7, v7
	v_add_f32_e32 v6, 1.0, v6
	v_add_f32_e32 v7, 1.0, v7
	v_rcp_f32_e32 v6, v6
	v_rcp_f32_e32 v7, v7
	s_nop 0
	v_pk_mul_f32 v[0:1], v[0:1], v[6:7]
	s_nop 0
	v_pk_mul_f32 v[6:7], v[2:3], v[0:1]
	v_mov_b64_e32 v[0:1], s[6:7]
	v_mad_i64_i32 v[0:1], s[0:1], v18, s30, v[0:1]
	v_lshl_add_u64 v[12:13], v[138:139], 1, v[0:1]
	v_cvt_pk_bf16_f32 v0, v8, v9
	v_cvt_pk_bf16_f32 v1, v10, v11
	v_cvt_pk_bf16_f32 v2, v4, v5
	v_cvt_pk_bf16_f32 v3, v6, v7
	s_mov_b64 s[0:1], -1
	global_store_dwordx4 v[12:13], v[0:3], off
	s_branch .Lswiglu_join
